# P5 epilogue: ssq prefetched in last K-iteration, epilogue has no loads or waits
# baseline (speedup 1.0000x reference)
; #define PG8_LDA(dst, b, h) do { _Pragma("unroll") for (int m = 0; m < 4; ++m) _Pragma("unroll") for (int k = 0; k < 2; ++k) dst[m][k] = *(const LAS bf16x8*)(lds + PG8_SA(b, h) + aoff + m * 2048 + k * 1024); } while (0)
; template <class Epi, bool ALIGN_EPI, bool SPLITA>
; __device__ __forceinline__ void gemm_phase(LAS unsigned char* lds, const Gemm g, const StaticOrder& S, const Epi& E) {
;     ...
;                 a1 = (t + 1 < g.ksplit) ? cA + (size_t)(t + 1) * kstep : cA2 + (size_t)(t + 1 - g.ksplit) * 2048;
;                 a2 = last ? nA : ((t + 2 < g.ksplit) ? cA + (size_t)(t + 2) * kstep : cA2 + (size_t)(t + 2 - g.ksplit) * 2048);
;             } else { a1 = cA + kofs(t + 1); a2 = last ? nA : cA + kofs(t + 2); }
;             const char* b2 = last ? nB : cB + (size_t)(t + 2) * kstepB;
;             const bool s2a = SPLITA && (t + 1 >= g.ksplit), s2b = SPLITA && !last && (t + 2 >= g.ksplit);
;             const char* a3 = a2 + ((Epi::KSUB || s2b) ? (size_t)2048 : kstep); const char* b3 = b2 + kstepB;
;             const bool m1 = SPLITA && mirC && (t + 1 < g.ksplit), m2 = SPLITA && (last ? mirN : (mirC && (t + 2 < g.ksplit)));
;             const unsigned vo1[2] = {s2a ? voffA2[0] : m1 ? voffAm[0] : voffA[0], s2a ? voffA2[1] : m1 ? voffAm[1] : voffA[1]}, vo2[2] = {s2b ? voffA2[0] : m2 ? voffAm[0] : voffA[0], s2b ? voffA2[1] : m2 ? voffAm[1] : voffA[1]};
;             const char* a1h = m1 ? a1 - hstepA : a1 + hstepA; const char* a2h = m2 ? a2 - hstepA : a2 + hstepA;
;             PG8_LDB(B0, 0, 0); PG8_LDB(B1, 0, 1); PG8_SCHED; PG8_LDA(At, 0, 0); PG8_STAGE(PG8_SA(1, 1), a1h, vo1);
;             PG8_WAIT_V(8); PG8_WAIT_L(0); PG8_BAR; PG8_MMA(0, 0, At, B0); PG8_MMA(0, 1, At, B1); PG8_BAR; PG8_SCHED;
;             PG8_LDA(At, 0, 1); PG8_STAGE(PG8_SB(0, 0), b2, voffB); PG8_STAGE(PG8_SB(0, 1), b2 + hstepB, voffB); PG8_STAGE(PG8_SA(0, 0), a2, vo2);
;             PG8_WAIT_V(8); PG8_WAIT_L(0); PG8_BAR; PG8_MMA(1, 0, At, B0); PG8_MMA(1, 1, At, B1); PG8_BAR; PG8_SCHED;
;             PG8_LDB(B0, 1, 0); PG8_LDB(B1, 1, 1); PG8_SCHED; PG8_LDA(At, 1, 0); PG8_STAGE(PG8_SA(0, 1), a2h, vo2);
;     __device__ __forceinline__ void operator()(const Acc& acc, const Unit& u, int wr, int wc, int fr, int fq) const {
;     ...
;                 const int row = row0 + ai * HALF + m * 16; const float rinv = __builtin_amdgcn_rsqf(ssq[row] * (1.0f / DM) + EPS);
.LBB0_796:
	ds_read_b128 v[150:153], v155
	ds_read_b128 v[160:163], v155 offset:1024
	ds_read_b128 v[164:167], v155 offset:2048
	ds_read_b128 v[168:171], v155 offset:3072
	ds_read_b128 v[172:175], v156
	ds_read_b128 v[176:179], v156 offset:1024
	ds_read_b128 v[180:183], v156 offset:2048
	ds_read_b128 v[184:187], v156 offset:3072
	s_add_u32 s12, s36, 0xfffc0080
	s_addc_u32 s13, s37, -1
	s_cmp_eq_u32 s57, 12
	s_cselect_b32 s41, s19, s13
	s_cselect_b32 s40, s29, s12
	s_cselect_b32 s39, s21, s56
	s_cselect_b32 s38, s31, s55
	s_cselect_b32 s99, 1, 0
	v_lshl_add_u64 v[220:221], s[36:37], 0, v[140:141]
	s_add_i32 m0, s42, 0xc000
	ds_read_b128 v[188:191], v157
	ds_read_b128 v[192:195], v157 offset:1024
	ds_read_b128 v[196:199], v157 offset:2048
	ds_read_b128 v[200:203], v157 offset:3072
	ds_read_b128 v[204:207], v157 offset:4096
	ds_read_b128 v[208:211], v157 offset:5120
	ds_read_b128 v[212:215], v157 offset:6144
	ds_read_b128 v[216:219], v157 offset:7168
	global_load_lds_dwordx4 v[220:221], off
	v_lshl_add_u64 v[220:221], s[36:37], 0, v[142:143]
	s_add_i32 m0, s42, 0xe000
	s_nop 0
	global_load_lds_dwordx4 v[220:221], off
	s_waitcnt vmcnt(8)
	s_waitcnt lgkmcnt(0)
	s_cmp_lg_u32 s99, 0
	s_cbranch_scc0 .Lp5_nopf
	v_lshl_add_u32 v238, s28, 8, v1
	v_lshlrev_b32_e32 v238, 2, v238
	global_load_dword v230, v238, s[66:67]
	global_load_dword v231, v238, s[66:67] offset:64
	global_load_dword v232, v238, s[66:67] offset:128
	global_load_dword v233, v238, s[66:67] offset:192
	global_load_dword v234, v238, s[66:67] offset:512
	global_load_dword v235, v238, s[66:67] offset:576
	global_load_dword v236, v238, s[66:67] offset:640
	global_load_dword v237, v238, s[66:67] offset:704
.Lp5_nopf:
	s_barrier
	s_setprio 1
	s_waitcnt lgkmcnt(0)
	v_mfma_f32_16x16x32_bf16 v[126:129], v[150:153], v[188:191], v[126:129]
	v_mfma_f32_16x16x32_bf16 v[122:125], v[164:167], v[188:191], v[122:125]
	v_mfma_f32_16x16x32_bf16 v[110:113], v[150:153], v[196:199], v[110:113]
	v_mfma_f32_16x16x32_bf16 v[106:109], v[164:167], v[196:199], v[106:109]
	v_mfma_f32_16x16x32_bf16 v[94:97], v[150:153], v[204:207], v[94:97]
	v_mfma_f32_16x16x32_bf16 v[90:93], v[164:167], v[204:207], v[90:93]
	v_mfma_f32_16x16x32_bf16 v[78:81], v[150:153], v[212:215], v[78:81]
	v_mfma_f32_16x16x32_bf16 v[74:77], v[164:167], v[212:215], v[74:77]
	v_mfma_f32_16x16x32_bf16 v[126:129], v[160:163], v[192:195], v[126:129]
	v_mfma_f32_16x16x32_bf16 v[122:125], v[168:171], v[192:195], v[122:125]
	v_mfma_f32_16x16x32_bf16 v[110:113], v[160:163], v[200:203], v[110:113]
	v_mfma_f32_16x16x32_bf16 v[106:109], v[168:171], v[200:203], v[106:109]
	v_mfma_f32_16x16x32_bf16 v[94:97], v[160:163], v[208:211], v[94:97]
	v_mfma_f32_16x16x32_bf16 v[90:93], v[168:171], v[208:211], v[90:93]
	v_mfma_f32_16x16x32_bf16 v[78:81], v[160:163], v[216:219], v[78:81]
	v_mfma_f32_16x16x32_bf16 v[74:77], v[168:171], v[216:219], v[74:77]
	s_setprio 0
	s_setprio 1
	v_mfma_f32_16x16x32_bf16 v[118:121], v[172:175], v[188:191], v[118:121]
	v_mfma_f32_16x16x32_bf16 v[114:117], v[180:183], v[188:191], v[114:117]
	v_mfma_f32_16x16x32_bf16 v[102:105], v[172:175], v[196:199], v[102:105]
	v_mfma_f32_16x16x32_bf16 v[98:101], v[180:183], v[196:199], v[98:101]
	v_mfma_f32_16x16x32_bf16 v[86:89], v[172:175], v[204:207], v[86:89]
	v_mfma_f32_16x16x32_bf16 v[82:85], v[180:183], v[204:207], v[82:85]
	v_mfma_f32_16x16x32_bf16 v[70:73], v[172:175], v[212:215], v[70:73]
	v_mfma_f32_16x16x32_bf16 v[66:69], v[180:183], v[212:215], v[66:69]
	v_mfma_f32_16x16x32_bf16 v[118:121], v[176:179], v[192:195], v[118:121]
	v_mfma_f32_16x16x32_bf16 v[114:117], v[184:187], v[192:195], v[114:117]
	v_mfma_f32_16x16x32_bf16 v[102:105], v[176:179], v[200:203], v[102:105]
	v_mfma_f32_16x16x32_bf16 v[98:101], v[184:187], v[200:203], v[98:101]
	v_mfma_f32_16x16x32_bf16 v[86:89], v[176:179], v[208:211], v[86:89]
	v_mfma_f32_16x16x32_bf16 v[82:85], v[184:187], v[208:211], v[82:85]
	v_mfma_f32_16x16x32_bf16 v[70:73], v[176:179], v[216:219], v[70:73]
	v_mfma_f32_16x16x32_bf16 v[66:69], v[184:187], v[216:219], v[66:69]
	s_setprio 0
	s_barrier
	s_add_i32 s12, s51, s6
	v_lshl_add_u64 v[220:221], s[38:39], 0, v[134:135]
	s_mov_b32 m0, s12
	ds_read_b128 v[188:191], v157 offset:16384
	ds_read_b128 v[192:195], v157 offset:17408
	ds_read_b128 v[196:199], v157 offset:18432
	ds_read_b128 v[200:203], v157 offset:19456
	ds_read_b128 v[204:207], v157 offset:20480
	ds_read_b128 v[208:211], v157 offset:21504
	ds_read_b128 v[212:215], v157 offset:22528
	ds_read_b128 v[216:219], v157 offset:23552
	global_load_lds_dwordx4 v[220:221], off
	s_add_i32 m0, s12, 0x2000
	s_add_u32 s12, s38, 0x40000
	v_lshl_add_u64 v[222:223], s[38:39], 0, v[130:131]
	s_addc_u32 s13, s39, 0
	s_add_i32 s60, s52, s6
	global_load_lds_dwordx4 v[222:223], off
	v_lshl_add_u64 v[224:225], s[12:13], 0, v[134:135]
	s_mov_b32 m0, s60
	v_lshl_add_u64 v[226:227], s[40:41], 0, v[132:133]
	global_load_lds_dwordx4 v[224:225], off
	v_lshl_add_u64 v[224:225], s[12:13], 0, v[130:131]
	s_add_i32 m0, s60, 0x2000
	s_nop 0
	global_load_lds_dwordx4 v[224:225], off
	v_lshl_add_u64 v[224:225], s[40:41], 0, v[136:137]
	s_mov_b32 m0, s42
	s_nop 0
	global_load_lds_dwordx4 v[224:225], off
	s_mov_b32 m0, s43
	s_nop 0
	global_load_lds_dwordx4 v[226:227], off
	s_cmp_lg_u32 s99, 0
	s_cbranch_scc1 .Lp5_w16
	s_waitcnt vmcnt(8)
	s_branch .Lp5_wd
.Lp5_w16:
	s_waitcnt vmcnt(16)
; #define PG8_STAGE(bufoff, gbase, voff) do { _Pragma("unroll") for (int _i = 0; _i < 2; ++_i) \
;         __builtin_amdgcn_global_load_lds((const unsigned*)((const char*)(gbase) + (voff)[_i]), (LAS unsigned*)(lds + (bufoff) + ldsw + _i * 8192), 16, 0, 0); } while (0)
; #define PG8_LDA(dst, b, h) do { _Pragma("unroll") for (int m = 0; m < 4; ++m) _Pragma("unroll") for (int k = 0; k < 2; ++k) dst[m][k] = *(const LAS bf16x8*)(lds + PG8_SA(b, h) + aoff + m * 2048 + k * 1024); } while (0)
; #define PG8_LDB(dst, b, h) do { _Pragma("unroll") for (int n = 0; n < 2; ++n) _Pragma("unroll") for (int k = 0; k < 2; ++k) dst[n][k] = *(const LAS bf16x8*)(lds + PG8_SB(b, h) + boff + n * 2048 + k * 1024); } while (0)
; #define PG8_MMA(ai, bj, At, Bt) do { __builtin_amdgcn_s_setprio(1); _Pragma("unroll") for (int m = 0; m < 4; ++m) _Pragma("unroll") for (int n = 0; n < 2; ++n) _Pragma("unroll") for (int k = 0; k < 2; ++k) \
;         acc[ai][bj][m][n] = __builtin_amdgcn_mfma_f32_16x16x32_bf16(Bt[n][k], At[m][k], acc[ai][bj][m][n], 0, 0, 0); __builtin_amdgcn_s_setprio(0); } while (0)
; #define PG8_WAIT_V(n) asm volatile("s_waitcnt vmcnt(" #n ")" ::: "memory")
; #define PG8_WAIT_L(n) asm volatile("s_waitcnt lgkmcnt(" #n ")" ::: "memory")
; #define PG8_BAR __builtin_amdgcn_s_barrier()
; #define PG8_SCHED __builtin_amdgcn_sched_barrier(0)
; template <class Epi, bool ALIGN_EPI, bool SPLITA>
; __device__ __forceinline__ void gemm_phase(LAS unsigned char* lds, const Gemm g, const StaticOrder& S, const Epi& E) {
;     ...
;             PG8_WAIT_V(8); PG8_WAIT_L(0); PG8_BAR; PG8_MMA(1, 0, At, B0); PG8_MMA(1, 1, At, B1); PG8_BAR; PG8_SCHED;
;             PG8_LDB(B0, 1, 0); PG8_LDB(B1, 1, 1); PG8_SCHED; PG8_LDA(At, 1, 0); PG8_STAGE(PG8_SA(0, 1), a2h, vo2);
;             PG8_WAIT_V(8); PG8_WAIT_L(0); PG8_BAR; PG8_MMA(0, 0, At, B0); PG8_MMA(0, 1, At, B1); PG8_BAR; PG8_SCHED;
;             PG8_LDA(At, 1, 1); PG8_STAGE(PG8_SB(1, 0), b3, voffB); PG8_STAGE(PG8_SB(1, 1), b3 + hstepB, voffB); PG8_STAGE(PG8_SA(1, 0), a3, vo2);
.Lp5_wd:
	s_waitcnt lgkmcnt(0)
	s_barrier
	s_setprio 1
	s_waitcnt lgkmcnt(0)
	v_mfma_f32_16x16x32_bf16 v[62:65], v[150:153], v[188:191], v[62:65]
	v_mfma_f32_16x16x32_bf16 v[58:61], v[164:167], v[188:191], v[58:61]
	v_mfma_f32_16x16x32_bf16 v[38:41], v[150:153], v[196:199], v[38:41]
	v_mfma_f32_16x16x32_bf16 v[34:37], v[164:167], v[196:199], v[34:37]
	v_mfma_f32_16x16x32_bf16 v[22:25], v[150:153], v[204:207], v[22:25]
	v_mfma_f32_16x16x32_bf16 v[18:21], v[164:167], v[204:207], v[18:21]
	v_mfma_f32_16x16x32_bf16 v[6:9], v[150:153], v[212:215], v[6:9]
	v_mfma_f32_16x16x32_bf16 v[2:5], v[164:167], v[212:215], v[2:5]
	v_mfma_f32_16x16x32_bf16 v[62:65], v[160:163], v[192:195], v[62:65]
	v_mfma_f32_16x16x32_bf16 v[58:61], v[168:171], v[192:195], v[58:61]
	v_mfma_f32_16x16x32_bf16 v[38:41], v[160:163], v[200:203], v[38:41]
	v_mfma_f32_16x16x32_bf16 v[34:37], v[168:171], v[200:203], v[34:37]
	v_mfma_f32_16x16x32_bf16 v[22:25], v[160:163], v[208:211], v[22:25]
	v_mfma_f32_16x16x32_bf16 v[18:21], v[168:171], v[208:211], v[18:21]
	v_mfma_f32_16x16x32_bf16 v[6:9], v[160:163], v[216:219], v[6:9]
	v_mfma_f32_16x16x32_bf16 v[2:5], v[168:171], v[216:219], v[2:5]
	s_setprio 0
	s_setprio 1
	v_mfma_f32_16x16x32_bf16 v[54:57], v[172:175], v[188:191], v[54:57]
	v_mfma_f32_16x16x32_bf16 v[50:53], v[180:183], v[188:191], v[50:53]
	v_mfma_f32_16x16x32_bf16 v[42:45], v[172:175], v[196:199], v[42:45]
	v_mfma_f32_16x16x32_bf16 v[46:49], v[180:183], v[196:199], v[46:49]
	v_mfma_f32_16x16x32_bf16 v[26:29], v[172:175], v[204:207], v[26:29]
	v_mfma_f32_16x16x32_bf16 v[30:33], v[180:183], v[204:207], v[30:33]
	v_mfma_f32_16x16x32_bf16 v[10:13], v[172:175], v[212:215], v[10:13]
	v_mfma_f32_16x16x32_bf16 v[14:17], v[180:183], v[212:215], v[14:17]
	v_mfma_f32_16x16x32_bf16 v[54:57], v[176:179], v[192:195], v[54:57]
	v_mfma_f32_16x16x32_bf16 v[50:53], v[184:187], v[192:195], v[50:53]
	v_mfma_f32_16x16x32_bf16 v[42:45], v[176:179], v[200:203], v[42:45]
	v_mfma_f32_16x16x32_bf16 v[46:49], v[184:187], v[200:203], v[46:49]
	v_mfma_f32_16x16x32_bf16 v[26:29], v[176:179], v[208:211], v[26:29]
	v_mfma_f32_16x16x32_bf16 v[30:33], v[184:187], v[208:211], v[30:33]
	v_mfma_f32_16x16x32_bf16 v[10:13], v[176:179], v[216:219], v[10:13]
	v_mfma_f32_16x16x32_bf16 v[14:17], v[184:187], v[216:219], v[14:17]
	s_setprio 0
	s_barrier
	s_add_i32 s60, 0, 0x18000
	v_add_u32_e32 v149, s60, v154
	s_add_i32 s61, 0, 0x1c000
	ds_read_b128 v[150:153], v149
	ds_read_b128 v[160:163], v149 offset:1024
	ds_read_b128 v[164:167], v149 offset:2048
	ds_read_b128 v[168:171], v149 offset:3072
	v_add_u32_e32 v149, s61, v154
	ds_read_b128 v[172:175], v149
	ds_read_b128 v[176:179], v149 offset:1024
	ds_read_b128 v[180:183], v149 offset:2048
	ds_read_b128 v[184:187], v149 offset:3072
	s_add_u32 s12, s40, 0x40000
	s_addc_u32 s13, s41, 0
	s_mov_b32 m0, s44
	v_lshl_add_u64 v[228:229], s[12:13], 0, v[136:137]
	ds_read_b128 v[188:191], v157 offset:32768
	ds_read_b128 v[192:195], v157 offset:33792
	ds_read_b128 v[196:199], v157 offset:34816
	ds_read_b128 v[200:203], v157 offset:35840
	ds_read_b128 v[204:207], v157 offset:36864
	ds_read_b128 v[208:211], v157 offset:37888
	ds_read_b128 v[212:215], v157 offset:38912
	ds_read_b128 v[216:219], v157 offset:39936
	global_load_lds_dwordx4 v[228:229], off
	v_lshl_add_u64 v[228:229], s[12:13], 0, v[132:133]
	s_mov_b32 m0, s45
	s_nop 0
	global_load_lds_dwordx4 v[228:229], off
	s_waitcnt vmcnt(8)
	s_waitcnt lgkmcnt(0)
	s_barrier
	s_setprio 1
	s_waitcnt lgkmcnt(0)
	v_mfma_f32_16x16x32_bf16 v[126:129], v[150:153], v[188:191], v[126:129]
	v_mfma_f32_16x16x32_bf16 v[122:125], v[164:167], v[188:191], v[122:125]
	v_mfma_f32_16x16x32_bf16 v[110:113], v[150:153], v[196:199], v[110:113]
	v_mfma_f32_16x16x32_bf16 v[106:109], v[164:167], v[196:199], v[106:109]
	v_mfma_f32_16x16x32_bf16 v[94:97], v[150:153], v[204:207], v[94:97]
	v_mfma_f32_16x16x32_bf16 v[90:93], v[164:167], v[204:207], v[90:93]
	v_mfma_f32_16x16x32_bf16 v[78:81], v[150:153], v[212:215], v[78:81]
	v_mfma_f32_16x16x32_bf16 v[74:77], v[164:167], v[212:215], v[74:77]
	v_mfma_f32_16x16x32_bf16 v[126:129], v[160:163], v[192:195], v[126:129]
	v_mfma_f32_16x16x32_bf16 v[122:125], v[168:171], v[192:195], v[122:125]
	v_mfma_f32_16x16x32_bf16 v[110:113], v[160:163], v[200:203], v[110:113]
	v_mfma_f32_16x16x32_bf16 v[106:109], v[168:171], v[200:203], v[106:109]
	v_mfma_f32_16x16x32_bf16 v[94:97], v[160:163], v[208:211], v[94:97]
	v_mfma_f32_16x16x32_bf16 v[90:93], v[168:171], v[208:211], v[90:93]
	v_mfma_f32_16x16x32_bf16 v[78:81], v[160:163], v[216:219], v[78:81]
	v_mfma_f32_16x16x32_bf16 v[74:77], v[168:171], v[216:219], v[74:77]
	s_setprio 0
	s_setprio 1
	v_mfma_f32_16x16x32_bf16 v[118:121], v[172:175], v[188:191], v[118:121]
	v_mfma_f32_16x16x32_bf16 v[114:117], v[180:183], v[188:191], v[114:117]
	v_mfma_f32_16x16x32_bf16 v[102:105], v[172:175], v[196:199], v[102:105]
	v_mfma_f32_16x16x32_bf16 v[98:101], v[180:183], v[196:199], v[98:101]
	v_mfma_f32_16x16x32_bf16 v[86:89], v[172:175], v[204:207], v[86:89]
	v_mfma_f32_16x16x32_bf16 v[82:85], v[180:183], v[204:207], v[82:85]
	v_mfma_f32_16x16x32_bf16 v[70:73], v[172:175], v[212:215], v[70:73]
	v_mfma_f32_16x16x32_bf16 v[66:69], v[180:183], v[212:215], v[66:69]
	v_mfma_f32_16x16x32_bf16 v[118:121], v[176:179], v[192:195], v[118:121]
	v_mfma_f32_16x16x32_bf16 v[114:117], v[184:187], v[192:195], v[114:117]
	v_mfma_f32_16x16x32_bf16 v[102:105], v[176:179], v[200:203], v[102:105]
	v_mfma_f32_16x16x32_bf16 v[98:101], v[184:187], v[200:203], v[98:101]
	v_mfma_f32_16x16x32_bf16 v[86:89], v[176:179], v[208:211], v[86:89]
	v_mfma_f32_16x16x32_bf16 v[82:85], v[184:187], v[208:211], v[82:85]
	v_mfma_f32_16x16x32_bf16 v[70:73], v[176:179], v[216:219], v[70:73]
	v_mfma_f32_16x16x32_bf16 v[66:69], v[184:187], v[216:219], v[66:69]
	s_setprio 0
	s_barrier
; __device__ __forceinline__ u32x4 pack8(const f32x4 a, const f32x4 b) { u32x4 w; w.x = cvt_pk_bf16(a[0], a[1]); w.y = cvt_pk_bf16(a[2], a[3]); w.z = cvt_pk_bf16(b[0], b[1]); w.w = cvt_pk_bf16(b[2], b[3]); return w; }
; #define PG8_STAGE(bufoff, gbase, voff) do { _Pragma("unroll") for (int _i = 0; _i < 2; ++_i) \
;         __builtin_amdgcn_global_load_lds((const unsigned*)((const char*)(gbase) + (voff)[_i]), (LAS unsigned*)(lds + (bufoff) + ldsw + _i * 8192), 16, 0, 0); } while (0)
; #define PG8_LDA(dst, b, h) do { _Pragma("unroll") for (int m = 0; m < 4; ++m) _Pragma("unroll") for (int k = 0; k < 2; ++k) dst[m][k] = *(const LAS bf16x8*)(lds + PG8_SA(b, h) + aoff + m * 2048 + k * 1024); } while (0)
; #define PG8_WAIT_V(n) asm volatile("s_waitcnt vmcnt(" #n ")" ::: "memory")
; template <class Epi, bool ALIGN_EPI, bool SPLITA>
; __device__ __forceinline__ void gemm_phase(LAS unsigned char* lds, const Gemm g, const StaticOrder& S, const Epi& E) {
;     ...
;             PG8_WAIT_V(8); PG8_WAIT_L(0); PG8_BAR; PG8_MMA(0, 0, At, B0); PG8_MMA(0, 1, At, B1); PG8_BAR; PG8_SCHED;
;             PG8_LDA(At, 1, 1); PG8_STAGE(PG8_SB(1, 0), b3, voffB); PG8_STAGE(PG8_SB(1, 1), b3 + hstepB, voffB); PG8_STAGE(PG8_SA(1, 0), a3, vo2);
;             PG8_WAIT_V(8); PG8_WAIT_L(0); PG8_BAR; PG8_MMA(1, 0, At, B0); PG8_MMA(1, 1, At, B1); PG8_BAR; PG8_SCHED;
;         }
;         if constexpr (ALIGN_EPI) { if (wr == 0) PG8_BAR; }
;         E(acc, cur, wr, wc, fr, fq);
;     __device__ __forceinline__ void operator()(const Acc& acc, const Unit& u, int wr, int wc, int fr, int fq) const {
;     ...
;         for (int ai = 0; ai < 2; ++ai)
; #pragma unroll
;             for (int m = 0; m < 4; ++m) {
;                 const int row = row0 + ai * HALF + m * 16; const float rinv = __builtin_amdgcn_rsqf(ssq[row] * (1.0f / DM) + EPS);
;                 bf16_t* rowp = U + (size_t)u.pm * (BM * FF) + (size_t)u.pn * (BM * BM) + (size_t)(((row & (BM - 1)) >> 4) * 8 + wc) * 512 + fr * 32 + 8 * fq;
; #pragma unroll
;                 for (int bj = 0; bj < 2; ++bj) { f32x4 v0 = acc[ai][bj][m][0] * rinv, v1 = acc[ai][bj][m][1] * rinv;
; #pragma unroll
;                     for (int e = 0; e < 4; ++e) { const float a = fmaxf(v0[e], 0.f), b = fmaxf(v1[e], 0.f); v0[e] = a * a; v1[e] = b * b; }
;                     __builtin_nontemporal_store(pack8(v0, v1), (u32x4*)(rowp + bj * (4 * 512))); }
	s_add_i32 s12, s60, s6
	v_lshl_add_u64 v[220:221], v[220:221], 0, s[8:9]
	s_mov_b32 m0, s12
	ds_read_b128 v[188:191], v157 offset:49152
	ds_read_b128 v[192:195], v157 offset:50176
	ds_read_b128 v[196:199], v157 offset:51200
	ds_read_b128 v[200:203], v157 offset:52224
	ds_read_b128 v[204:207], v157 offset:53248
	ds_read_b128 v[208:211], v157 offset:54272
	ds_read_b128 v[212:215], v157 offset:55296
	ds_read_b128 v[216:219], v157 offset:56320
	global_load_lds_dwordx4 v[220:221], off
	s_add_i32 m0, s12, 0x2000
	s_add_u32 s12, s38, 0x40800
	v_lshl_add_u64 v[220:221], v[222:223], 0, s[8:9]
	s_addc_u32 s13, s39, 0
	s_add_i32 s38, s61, s6
	global_load_lds_dwordx4 v[220:221], off
	v_lshl_add_u64 v[220:221], s[12:13], 0, v[134:135]
	s_mov_b32 m0, s38
	s_nop 0
	global_load_lds_dwordx4 v[220:221], off
	v_lshl_add_u64 v[220:221], s[12:13], 0, v[130:131]
	s_add_i32 m0, s38, 0x2000
	s_nop 0
	global_load_lds_dwordx4 v[220:221], off
	v_lshl_add_u64 v[220:221], v[224:225], 0, s[10:11]
	s_mov_b32 m0, s49
	s_nop 0
	global_load_lds_dwordx4 v[220:221], off
	v_lshl_add_u64 v[220:221], v[226:227], 0, s[10:11]
	s_mov_b32 m0, s50
	s_nop 0
	global_load_lds_dwordx4 v[220:221], off
	s_waitcnt vmcnt(8)
	s_waitcnt lgkmcnt(0)
	s_barrier
	s_setprio 1
	s_waitcnt lgkmcnt(0)
	v_mfma_f32_16x16x32_bf16 v[62:65], v[150:153], v[188:191], v[62:65]
	v_mfma_f32_16x16x32_bf16 v[58:61], v[164:167], v[188:191], v[58:61]
	v_mfma_f32_16x16x32_bf16 v[38:41], v[150:153], v[196:199], v[38:41]
	v_mfma_f32_16x16x32_bf16 v[34:37], v[164:167], v[196:199], v[34:37]
	v_mfma_f32_16x16x32_bf16 v[22:25], v[150:153], v[204:207], v[22:25]
	v_mfma_f32_16x16x32_bf16 v[18:21], v[164:167], v[204:207], v[18:21]
	v_mfma_f32_16x16x32_bf16 v[6:9], v[150:153], v[212:215], v[6:9]
	v_mfma_f32_16x16x32_bf16 v[2:5], v[164:167], v[212:215], v[2:5]
	v_mfma_f32_16x16x32_bf16 v[62:65], v[160:163], v[192:195], v[62:65]
	v_mfma_f32_16x16x32_bf16 v[58:61], v[168:171], v[192:195], v[58:61]
	v_mfma_f32_16x16x32_bf16 v[38:41], v[160:163], v[200:203], v[38:41]
	v_mfma_f32_16x16x32_bf16 v[34:37], v[168:171], v[200:203], v[34:37]
	v_mfma_f32_16x16x32_bf16 v[22:25], v[160:163], v[208:211], v[22:25]
	v_mfma_f32_16x16x32_bf16 v[18:21], v[168:171], v[208:211], v[18:21]
	v_mfma_f32_16x16x32_bf16 v[6:9], v[160:163], v[216:219], v[6:9]
	v_mfma_f32_16x16x32_bf16 v[2:5], v[168:171], v[216:219], v[2:5]
	s_setprio 0
	s_setprio 1
	v_mfma_f32_16x16x32_bf16 v[54:57], v[172:175], v[188:191], v[54:57]
	v_mfma_f32_16x16x32_bf16 v[50:53], v[180:183], v[188:191], v[50:53]
	v_mfma_f32_16x16x32_bf16 v[42:45], v[172:175], v[196:199], v[42:45]
	v_mfma_f32_16x16x32_bf16 v[46:49], v[180:183], v[196:199], v[46:49]
	v_mfma_f32_16x16x32_bf16 v[26:29], v[172:175], v[204:207], v[26:29]
	v_mfma_f32_16x16x32_bf16 v[30:33], v[180:183], v[204:207], v[30:33]
	v_mfma_f32_16x16x32_bf16 v[10:13], v[172:175], v[212:215], v[10:13]
	v_mfma_f32_16x16x32_bf16 v[14:17], v[180:183], v[212:215], v[14:17]
	v_mfma_f32_16x16x32_bf16 v[54:57], v[176:179], v[192:195], v[54:57]
	v_mfma_f32_16x16x32_bf16 v[50:53], v[184:187], v[192:195], v[50:53]
	v_mfma_f32_16x16x32_bf16 v[42:45], v[176:179], v[200:203], v[42:45]
	v_mfma_f32_16x16x32_bf16 v[46:49], v[184:187], v[200:203], v[46:49]
	v_mfma_f32_16x16x32_bf16 v[26:29], v[176:179], v[208:211], v[26:29]
	v_mfma_f32_16x16x32_bf16 v[30:33], v[184:187], v[208:211], v[30:33]
	v_mfma_f32_16x16x32_bf16 v[10:13], v[176:179], v[216:219], v[10:13]
	v_mfma_f32_16x16x32_bf16 v[14:17], v[184:187], v[216:219], v[14:17]
	s_setprio 0
	s_barrier
	s_add_i32 s57, s57, 2
	s_add_u32 s55, s55, 0x1000
	s_addc_u32 s56, s56, 0
	s_add_u32 s36, s36, 0x100
	s_addc_u32 s37, s37, 0
	s_cmp_gt_u32 s57, 13
	s_cbranch_scc0 .LBB0_796
	s_and_b64 vcc, exec, s[16:17]
	s_cbranch_vccz .LBB0_799
	s_barrier
.LBB0_799:
	v_lshl_add_u32 v150, s28, 8, v1
	v_ashrrev_i32_e32 v151, 31, v150
	v_lshl_add_u64 v[152:153], v[150:151], 2, s[66:67]
	s_nop 0
	s_ashr_i32 s29, s28, 31
	s_ashr_i32 s31, s30, 31
	s_lshl_b64 s[12:13], s[28:29], 21
	s_lshl_b64 s[28:29], s[30:31], 17
	s_add_u32 s12, s82, s12
	s_addc_u32 s13, s83, s13
	s_add_u32 s28, s12, s28
	s_addc_u32 s29, s13, s29
	s_add_u32 s12, s28, s53
	s_addc_u32 s13, s29, 0
	v_mov_b32_e32 v149, v139
	v_lshl_add_u64 v[164:165], s[12:13], 0, v[138:139]
	v_or_b32_e32 v160, 16, v150
	v_lshl_add_u64 v[164:165], v[164:165], 0, v[148:149]
	v_ashrrev_i32_e32 v161, 31, v160
	v_add_co_u32_e32 v168, vcc, s54, v164
	v_lshl_add_u64 v[162:163], v[160:161], 2, s[66:67]
	s_nop 0
	v_addc_co_u32_e32 v169, vcc, 0, v165, vcc
	s_nop 0
	v_fmamk_f32 v151, v230, 0x3a800000, v158
	v_rsq_f32_e32 v166, v151
	s_nop 0
	v_pk_mul_f32 v[128:129], v[128:129], v[166:167] op_sel_hi:[1,0]
	v_pk_mul_f32 v[126:127], v[126:127], v[166:167] op_sel_hi:[1,0]
	v_pk_mul_f32 v[124:125], v[124:125], v[166:167] op_sel_hi:[1,0]
	v_pk_mul_f32 v[122:123], v[122:123], v[166:167] op_sel_hi:[1,0]
	v_pk_mul_f32 v[120:121], v[120:121], v[166:167] op_sel_hi:[1,0]
	v_pk_mul_f32 v[118:119], v[118:119], v[166:167] op_sel_hi:[1,0]
	v_pk_mul_f32 v[116:117], v[116:117], v[166:167] op_sel_hi:[1,0]
	v_pk_mul_f32 v[114:115], v[114:115], v[166:167] op_sel_hi:[1,0]
	v_max_f32_e32 v126, 0, v126
	v_max_f32_e32 v122, 0, v122
	v_max_f32_e32 v127, 0, v127
	v_max_f32_e32 v123, 0, v123
	v_max_f32_e32 v128, 0, v128
	v_max_f32_e32 v124, 0, v124
	v_max_f32_e32 v129, 0, v129
	v_max_f32_e32 v125, 0, v125
	v_max_f32_e32 v118, 0, v118
	v_max_f32_e32 v114, 0, v114
	v_max_f32_e32 v119, 0, v119
	v_max_f32_e32 v115, 0, v115
	v_max_f32_e32 v120, 0, v120
	v_max_f32_e32 v116, 0, v116
	v_max_f32_e32 v121, 0, v121
	v_max_f32_e32 v117, 0, v117
	v_pk_mul_f32 v[126:127], v[126:127], v[126:127]
	v_pk_mul_f32 v[122:123], v[122:123], v[122:123]
; __device__ __forceinline__ u32x4 pack8(const f32x4 a, const f32x4 b) { u32x4 w; w.x = cvt_pk_bf16(a[0], a[1]); w.y = cvt_pk_bf16(a[2], a[3]); w.z = cvt_pk_bf16(b[0], b[1]); w.w = cvt_pk_bf16(b[2], b[3]); return w; }
;     __device__ __forceinline__ void operator()(const Acc& acc, const Unit& u, int wr, int wc, int fr, int fq) const {
;     ...
;         for (int ai = 0; ai < 2; ++ai)
; #pragma unroll
;             for (int m = 0; m < 4; ++m) {
;                 const int row = row0 + ai * HALF + m * 16; const float rinv = __builtin_amdgcn_rsqf(ssq[row] * (1.0f / DM) + EPS);
;                 bf16_t* rowp = U + (size_t)u.pm * (BM * FF) + (size_t)u.pn * (BM * BM) + (size_t)(((row & (BM - 1)) >> 4) * 8 + wc) * 512 + fr * 32 + 8 * fq;
; #pragma unroll
;                 for (int bj = 0; bj < 2; ++bj) { f32x4 v0 = acc[ai][bj][m][0] * rinv, v1 = acc[ai][bj][m][1] * rinv;
; #pragma unroll
;                     for (int e = 0; e < 4; ++e) { const float a = fmaxf(v0[e], 0.f), b = fmaxf(v1[e], 0.f); v0[e] = a * a; v1[e] = b * b; }
;                     __builtin_nontemporal_store(pack8(v0, v1), (u32x4*)(rowp + bj * (4 * 512))); }
	v_pk_mul_f32 v[128:129], v[128:129], v[128:129]
	v_pk_mul_f32 v[124:125], v[124:125], v[124:125]
	v_pk_mul_f32 v[118:119], v[118:119], v[118:119]
	v_pk_mul_f32 v[166:167], v[114:115], v[114:115]
	v_pk_mul_f32 v[120:121], v[120:121], v[120:121]
	v_pk_mul_f32 v[170:171], v[116:117], v[116:117]
	v_cvt_pk_bf16_f32 v114, v126, v127
	v_cvt_pk_bf16_f32 v115, v128, v129
	v_cvt_pk_bf16_f32 v116, v122, v123
	v_cvt_pk_bf16_f32 v117, v124, v125
	v_cvt_pk_bf16_f32 v118, v118, v119
	v_cvt_pk_bf16_f32 v119, v120, v121
	v_cvt_pk_bf16_f32 v120, v166, v167
	v_cvt_pk_bf16_f32 v121, v170, v171
	global_store_dwordx4 v[164:165], v[114:117], off nt
	global_store_dwordx4 v[168:169], v[118:121], off nt
	s_nop 0
	v_or_b32_e32 v116, 32, v150
	v_ashrrev_i32_e32 v117, 31, v116
	v_lshl_add_u64 v[118:119], v[116:117], 2, s[66:67]
	v_lshrrev_b32_e32 v114, 1, v160
	v_and_b32_e32 v114, 0x68, v114
	v_or_b32_e32 v114, s48, v114
	v_mov_b32_e32 v115, v139
	v_lshlrev_b32_e32 v114, 10, v114
	v_lshl_add_u64 v[114:115], s[28:29], 0, v[114:115]
	v_lshl_add_u64 v[114:115], v[114:115], 0, v[138:139]
	v_lshl_add_u64 v[114:115], v[114:115], 0, v[148:149]
	v_add_co_u32_e32 v122, vcc, s54, v114
	s_nop 0
	v_fmamk_f32 v117, v231, 0x3a800000, v158
	v_rsq_f32_e32 v120, v117
	v_addc_co_u32_e32 v123, vcc, 0, v115, vcc
	v_pk_mul_f32 v[112:113], v[112:113], v[120:121] op_sel_hi:[1,0]
	v_pk_mul_f32 v[110:111], v[110:111], v[120:121] op_sel_hi:[1,0]
	v_pk_mul_f32 v[108:109], v[108:109], v[120:121] op_sel_hi:[1,0]
	v_pk_mul_f32 v[106:107], v[106:107], v[120:121] op_sel_hi:[1,0]
	v_pk_mul_f32 v[104:105], v[104:105], v[120:121] op_sel_hi:[1,0]
	v_pk_mul_f32 v[102:103], v[102:103], v[120:121] op_sel_hi:[1,0]
	v_pk_mul_f32 v[100:101], v[100:101], v[120:121] op_sel_hi:[1,0]
	v_pk_mul_f32 v[98:99], v[98:99], v[120:121] op_sel_hi:[1,0]
	v_max_f32_e32 v110, 0, v110
	v_max_f32_e32 v106, 0, v106
	v_max_f32_e32 v111, 0, v111
	v_max_f32_e32 v107, 0, v107
	v_max_f32_e32 v112, 0, v112
	v_max_f32_e32 v108, 0, v108
	v_max_f32_e32 v113, 0, v113
	v_max_f32_e32 v109, 0, v109
	v_max_f32_e32 v102, 0, v102
	v_max_f32_e32 v98, 0, v98
	v_max_f32_e32 v103, 0, v103
	v_max_f32_e32 v99, 0, v99
	v_max_f32_e32 v104, 0, v104
	v_max_f32_e32 v100, 0, v100
	v_max_f32_e32 v105, 0, v105
	v_max_f32_e32 v101, 0, v101
	v_pk_mul_f32 v[110:111], v[110:111], v[110:111]
	v_pk_mul_f32 v[106:107], v[106:107], v[106:107]
	v_pk_mul_f32 v[112:113], v[112:113], v[112:113]
	v_pk_mul_f32 v[108:109], v[108:109], v[108:109]
	v_pk_mul_f32 v[102:103], v[102:103], v[102:103]
	v_pk_mul_f32 v[120:121], v[98:99], v[98:99]
	v_pk_mul_f32 v[104:105], v[104:105], v[104:105]
	v_pk_mul_f32 v[124:125], v[100:101], v[100:101]
	v_cvt_pk_bf16_f32 v98, v110, v111
	v_cvt_pk_bf16_f32 v99, v112, v113
	v_cvt_pk_bf16_f32 v100, v106, v107
	v_cvt_pk_bf16_f32 v101, v108, v109
	v_cvt_pk_bf16_f32 v102, v102, v103
	v_cvt_pk_bf16_f32 v103, v104, v105
	v_cvt_pk_bf16_f32 v104, v120, v121
	v_cvt_pk_bf16_f32 v105, v124, v125
	global_store_dwordx4 v[114:115], v[98:101], off nt
	global_store_dwordx4 v[122:123], v[102:105], off nt
	s_nop 0
	v_or_b32_e32 v100, 48, v150
	v_ashrrev_i32_e32 v101, 31, v100
	v_lshl_add_u64 v[102:103], v[100:101], 2, s[66:67]
	v_lshrrev_b32_e32 v98, 1, v116
	v_and_b32_e32 v98, 0x70, v98
	v_or_b32_e32 v98, s48, v98
	v_mov_b32_e32 v99, v139
	v_lshlrev_b32_e32 v98, 10, v98
	v_lshl_add_u64 v[98:99], s[28:29], 0, v[98:99]
	v_lshl_add_u64 v[98:99], v[98:99], 0, v[138:139]
	v_lshl_add_u64 v[98:99], v[98:99], 0, v[148:149]
	v_add_co_u32_e32 v106, vcc, s54, v98
	s_nop 0
	v_fmamk_f32 v101, v232, 0x3a800000, v158
	v_rsq_f32_e32 v104, v101
	v_addc_co_u32_e32 v107, vcc, 0, v99, vcc
	v_pk_mul_f32 v[96:97], v[96:97], v[104:105] op_sel_hi:[1,0]
	v_pk_mul_f32 v[94:95], v[94:95], v[104:105] op_sel_hi:[1,0]
	v_pk_mul_f32 v[92:93], v[92:93], v[104:105] op_sel_hi:[1,0]
	v_pk_mul_f32 v[90:91], v[90:91], v[104:105] op_sel_hi:[1,0]
	v_pk_mul_f32 v[88:89], v[88:89], v[104:105] op_sel_hi:[1,0]
	v_pk_mul_f32 v[86:87], v[86:87], v[104:105] op_sel_hi:[1,0]
	v_pk_mul_f32 v[84:85], v[84:85], v[104:105] op_sel_hi:[1,0]
	v_pk_mul_f32 v[82:83], v[82:83], v[104:105] op_sel_hi:[1,0]
	v_max_f32_e32 v94, 0, v94
	v_max_f32_e32 v90, 0, v90
	v_max_f32_e32 v95, 0, v95
	v_max_f32_e32 v91, 0, v91
	v_max_f32_e32 v96, 0, v96
	v_max_f32_e32 v92, 0, v92
	v_max_f32_e32 v97, 0, v97
	v_max_f32_e32 v93, 0, v93
	v_max_f32_e32 v86, 0, v86
	v_max_f32_e32 v82, 0, v82
	v_max_f32_e32 v87, 0, v87
	v_max_f32_e32 v83, 0, v83
	v_max_f32_e32 v88, 0, v88
	v_max_f32_e32 v84, 0, v84
	v_max_f32_e32 v89, 0, v89
	v_max_f32_e32 v85, 0, v85
	v_pk_mul_f32 v[94:95], v[94:95], v[94:95]
	v_pk_mul_f32 v[90:91], v[90:91], v[90:91]
	v_pk_mul_f32 v[96:97], v[96:97], v[96:97]
	v_pk_mul_f32 v[92:93], v[92:93], v[92:93]
	v_pk_mul_f32 v[86:87], v[86:87], v[86:87]
	v_pk_mul_f32 v[104:105], v[82:83], v[82:83]
	v_pk_mul_f32 v[88:89], v[88:89], v[88:89]
	v_pk_mul_f32 v[108:109], v[84:85], v[84:85]
	v_cvt_pk_bf16_f32 v82, v94, v95
	v_cvt_pk_bf16_f32 v83, v96, v97
	v_cvt_pk_bf16_f32 v84, v90, v91
	v_cvt_pk_bf16_f32 v85, v92, v93
	v_cvt_pk_bf16_f32 v86, v86, v87
	v_cvt_pk_bf16_f32 v87, v88, v89
	v_cvt_pk_bf16_f32 v88, v104, v105
	v_cvt_pk_bf16_f32 v89, v108, v109
	global_store_dwordx4 v[98:99], v[82:85], off nt
	global_store_dwordx4 v[106:107], v[86:89], off nt
	s_nop 0
	v_lshrrev_b32_e32 v82, 1, v100
	v_and_b32_e32 v82, 0x78, v82
	v_or_b32_e32 v82, s48, v82
	v_mov_b32_e32 v83, v139
	v_lshlrev_b32_e32 v82, 10, v82
	v_lshl_add_u64 v[82:83], s[28:29], 0, v[82:83]
	v_lshl_add_u64 v[82:83], v[82:83], 0, v[138:139]
	v_lshl_add_u64 v[82:83], v[82:83], 0, v[148:149]
	v_add_co_u32_e32 v86, vcc, s54, v82
	s_nop 0
	v_fmamk_f32 v84, v233, 0x3a800000, v158
; __device__ __forceinline__ u32x4 pack8(const f32x4 a, const f32x4 b) { u32x4 w; w.x = cvt_pk_bf16(a[0], a[1]); w.y = cvt_pk_bf16(a[2], a[3]); w.z = cvt_pk_bf16(b[0], b[1]); w.w = cvt_pk_bf16(b[2], b[3]); return w; }
;     __device__ __forceinline__ void operator()(const Acc& acc, const Unit& u, int wr, int wc, int fr, int fq) const {
;     ...
;         for (int ai = 0; ai < 2; ++ai)
; #pragma unroll
;             for (int m = 0; m < 4; ++m) {
;                 const int row = row0 + ai * HALF + m * 16; const float rinv = __builtin_amdgcn_rsqf(ssq[row] * (1.0f / DM) + EPS);
;                 bf16_t* rowp = U + (size_t)u.pm * (BM * FF) + (size_t)u.pn * (BM * BM) + (size_t)(((row & (BM - 1)) >> 4) * 8 + wc) * 512 + fr * 32 + 8 * fq;
; #pragma unroll
;                 for (int bj = 0; bj < 2; ++bj) { f32x4 v0 = acc[ai][bj][m][0] * rinv, v1 = acc[ai][bj][m][1] * rinv;
; #pragma unroll
;                     for (int e = 0; e < 4; ++e) { const float a = fmaxf(v0[e], 0.f), b = fmaxf(v1[e], 0.f); v0[e] = a * a; v1[e] = b * b; }
;                     __builtin_nontemporal_store(pack8(v0, v1), (u32x4*)(rowp + bj * (4 * 512))); }
	v_rsq_f32_e32 v84, v84
	v_addc_co_u32_e32 v87, vcc, 0, v83, vcc
	v_pk_mul_f32 v[80:81], v[80:81], v[84:85] op_sel_hi:[1,0]
	v_pk_mul_f32 v[78:79], v[78:79], v[84:85] op_sel_hi:[1,0]
	v_pk_mul_f32 v[76:77], v[76:77], v[84:85] op_sel_hi:[1,0]
	v_pk_mul_f32 v[74:75], v[74:75], v[84:85] op_sel_hi:[1,0]
	v_pk_mul_f32 v[72:73], v[72:73], v[84:85] op_sel_hi:[1,0]
	v_pk_mul_f32 v[70:71], v[70:71], v[84:85] op_sel_hi:[1,0]
	v_pk_mul_f32 v[68:69], v[68:69], v[84:85] op_sel_hi:[1,0]
	v_pk_mul_f32 v[66:67], v[66:67], v[84:85] op_sel_hi:[1,0]
	v_max_f32_e32 v78, 0, v78
	v_max_f32_e32 v74, 0, v74
	v_max_f32_e32 v79, 0, v79
	v_max_f32_e32 v75, 0, v75
	v_max_f32_e32 v80, 0, v80
	v_max_f32_e32 v76, 0, v76
	v_max_f32_e32 v81, 0, v81
	v_max_f32_e32 v77, 0, v77
	v_max_f32_e32 v70, 0, v70
	v_max_f32_e32 v66, 0, v66
	v_max_f32_e32 v71, 0, v71
	v_max_f32_e32 v67, 0, v67
	v_max_f32_e32 v72, 0, v72
	v_max_f32_e32 v68, 0, v68
	v_max_f32_e32 v73, 0, v73
	v_max_f32_e32 v69, 0, v69
	v_pk_mul_f32 v[78:79], v[78:79], v[78:79]
	v_pk_mul_f32 v[74:75], v[74:75], v[74:75]
	v_pk_mul_f32 v[80:81], v[80:81], v[80:81]
	v_pk_mul_f32 v[76:77], v[76:77], v[76:77]
	v_pk_mul_f32 v[70:71], v[70:71], v[70:71]
	v_pk_mul_f32 v[84:85], v[66:67], v[66:67]
	v_pk_mul_f32 v[72:73], v[72:73], v[72:73]
	v_pk_mul_f32 v[88:89], v[68:69], v[68:69]
	v_cvt_pk_bf16_f32 v66, v78, v79
	v_cvt_pk_bf16_f32 v67, v80, v81
	v_cvt_pk_bf16_f32 v68, v74, v75
	v_cvt_pk_bf16_f32 v69, v76, v77
	v_cvt_pk_bf16_f32 v70, v70, v71
	v_cvt_pk_bf16_f32 v71, v72, v73
	v_cvt_pk_bf16_f32 v72, v84, v85
	v_cvt_pk_bf16_f32 v73, v88, v89
	global_store_dwordx4 v[82:83], v[66:69], off nt
	global_store_dwordx4 v[86:87], v[70:73], off nt
	s_nop 0
	v_add_u32_e32 v66, 0x80, v150
	v_lshrrev_b32_e32 v66, 1, v66
	v_and_b32_e32 v66, 0x60, v66
	v_or_b32_e32 v66, s48, v66
	v_mov_b32_e32 v67, v139
	v_lshlrev_b32_e32 v66, 10, v66
	v_lshl_add_u64 v[66:67], s[28:29], 0, v[66:67]
	v_lshl_add_u64 v[66:67], v[66:67], 0, v[138:139]
	v_lshl_add_u64 v[66:67], v[66:67], 0, v[148:149]
	v_add_co_u32_e32 v70, vcc, s54, v66
	s_nop 0
	v_fmamk_f32 v68, v234, 0x3a800000, v158
	v_rsq_f32_e32 v68, v68
	v_addc_co_u32_e32 v71, vcc, 0, v67, vcc
	v_pk_mul_f32 v[64:65], v[64:65], v[68:69] op_sel_hi:[1,0]
	v_pk_mul_f32 v[62:63], v[62:63], v[68:69] op_sel_hi:[1,0]
	v_pk_mul_f32 v[60:61], v[60:61], v[68:69] op_sel_hi:[1,0]
	v_pk_mul_f32 v[58:59], v[58:59], v[68:69] op_sel_hi:[1,0]
	v_pk_mul_f32 v[56:57], v[56:57], v[68:69] op_sel_hi:[1,0]
	v_pk_mul_f32 v[54:55], v[54:55], v[68:69] op_sel_hi:[1,0]
	v_pk_mul_f32 v[52:53], v[52:53], v[68:69] op_sel_hi:[1,0]
	v_pk_mul_f32 v[50:51], v[50:51], v[68:69] op_sel_hi:[1,0]
	v_max_f32_e32 v62, 0, v62
	v_max_f32_e32 v58, 0, v58
	v_max_f32_e32 v63, 0, v63
	v_max_f32_e32 v59, 0, v59
	v_max_f32_e32 v64, 0, v64
	v_max_f32_e32 v60, 0, v60
	v_max_f32_e32 v65, 0, v65
	v_max_f32_e32 v61, 0, v61
	v_max_f32_e32 v54, 0, v54
	v_max_f32_e32 v50, 0, v50
	v_max_f32_e32 v55, 0, v55
	v_max_f32_e32 v51, 0, v51
	v_max_f32_e32 v56, 0, v56
	v_max_f32_e32 v52, 0, v52
	v_max_f32_e32 v57, 0, v57
	v_max_f32_e32 v53, 0, v53
	v_pk_mul_f32 v[62:63], v[62:63], v[62:63]
	v_pk_mul_f32 v[58:59], v[58:59], v[58:59]
	v_pk_mul_f32 v[64:65], v[64:65], v[64:65]
	v_pk_mul_f32 v[60:61], v[60:61], v[60:61]
	v_pk_mul_f32 v[54:55], v[54:55], v[54:55]
	v_pk_mul_f32 v[68:69], v[50:51], v[50:51]
	v_pk_mul_f32 v[56:57], v[56:57], v[56:57]
	v_pk_mul_f32 v[72:73], v[52:53], v[52:53]
	v_cvt_pk_bf16_f32 v50, v62, v63
	v_cvt_pk_bf16_f32 v51, v64, v65
	v_cvt_pk_bf16_f32 v52, v58, v59
	v_cvt_pk_bf16_f32 v53, v60, v61
	v_cvt_pk_bf16_f32 v54, v54, v55
	v_cvt_pk_bf16_f32 v55, v56, v57
	v_cvt_pk_bf16_f32 v56, v68, v69
	v_cvt_pk_bf16_f32 v57, v72, v73
	global_store_dwordx4 v[66:67], v[50:53], off nt
	global_store_dwordx4 v[70:71], v[54:57], off nt
	s_nop 0
	v_add_u32_e32 v50, 0x90, v150
	v_lshrrev_b32_e32 v50, 1, v50
	v_and_b32_e32 v50, 0x68, v50
	v_or_b32_e32 v50, s48, v50
	v_mov_b32_e32 v51, v139
	v_lshlrev_b32_e32 v50, 10, v50
	v_lshl_add_u64 v[50:51], s[28:29], 0, v[50:51]
	v_lshl_add_u64 v[50:51], v[50:51], 0, v[138:139]
	v_lshl_add_u64 v[50:51], v[50:51], 0, v[148:149]
	v_add_co_u32_e32 v54, vcc, s54, v50
	s_nop 0
	v_fmamk_f32 v52, v235, 0x3a800000, v158
	v_rsq_f32_e32 v52, v52
	v_addc_co_u32_e32 v55, vcc, 0, v51, vcc
	v_pk_mul_f32 v[40:41], v[40:41], v[52:53] op_sel_hi:[1,0]
	v_pk_mul_f32 v[38:39], v[38:39], v[52:53] op_sel_hi:[1,0]
	v_pk_mul_f32 v[36:37], v[36:37], v[52:53] op_sel_hi:[1,0]
	v_pk_mul_f32 v[34:35], v[34:35], v[52:53] op_sel_hi:[1,0]
	v_pk_mul_f32 v[44:45], v[44:45], v[52:53] op_sel_hi:[1,0]
	v_pk_mul_f32 v[42:43], v[42:43], v[52:53] op_sel_hi:[1,0]
	v_pk_mul_f32 v[48:49], v[48:49], v[52:53] op_sel_hi:[1,0]
	v_pk_mul_f32 v[46:47], v[46:47], v[52:53] op_sel_hi:[1,0]
	v_max_f32_e32 v38, 0, v38
	v_max_f32_e32 v34, 0, v34
	v_max_f32_e32 v39, 0, v39
	v_max_f32_e32 v35, 0, v35
	v_max_f32_e32 v40, 0, v40
	v_max_f32_e32 v36, 0, v36
	v_max_f32_e32 v41, 0, v41
	v_max_f32_e32 v37, 0, v37
	v_max_f32_e32 v42, 0, v42
	v_max_f32_e32 v46, 0, v46
	v_max_f32_e32 v43, 0, v43
	v_max_f32_e32 v47, 0, v47
	v_max_f32_e32 v44, 0, v44
; __device__ __forceinline__ u32x4 pack8(const f32x4 a, const f32x4 b) { u32x4 w; w.x = cvt_pk_bf16(a[0], a[1]); w.y = cvt_pk_bf16(a[2], a[3]); w.z = cvt_pk_bf16(b[0], b[1]); w.w = cvt_pk_bf16(b[2], b[3]); return w; }
; #define PG8_BAR __builtin_amdgcn_s_barrier()
; template <class Epi, bool ALIGN_EPI, bool SPLITA>
; __device__ __forceinline__ void gemm_phase(LAS unsigned char* lds, const Gemm g, const StaticOrder& S, const Epi& E) {
;     ...
;         if (!has_next) break;
; #pragma unroll
;         for (int a = 0; a < 2; ++a)
; #pragma unroll
;             for (int b = 0; b < 2; ++b)
; #pragma unroll
;                 for (int m = 0; m < 4; ++m)
; #pragma unroll
;                     for (int n = 0; n < 2; ++n) acc[a][b][m][n] = (f32x4){0.f, 0.f, 0.f, 0.f};
;         cur = nxt; cA = nA; cB = nB; mirC = mirN; if constexpr (SPLITA) cA2 = (const char*)g.A2 + (size_t)cur.pm * tstepA; ++ui;
;         if constexpr (ALIGN_EPI) { if (wr == 1) PG8_BAR; }
;     __device__ __forceinline__ void operator()(const Acc& acc, const Unit& u, int wr, int wc, int fr, int fq) const {
;     ...
;         for (int ai = 0; ai < 2; ++ai)
; #pragma unroll
;             for (int m = 0; m < 4; ++m) {
;                 const int row = row0 + ai * HALF + m * 16; const float rinv = __builtin_amdgcn_rsqf(ssq[row] * (1.0f / DM) + EPS);
;                 bf16_t* rowp = U + (size_t)u.pm * (BM * FF) + (size_t)u.pn * (BM * BM) + (size_t)(((row & (BM - 1)) >> 4) * 8 + wc) * 512 + fr * 32 + 8 * fq;
; #pragma unroll
;                 for (int bj = 0; bj < 2; ++bj) { f32x4 v0 = acc[ai][bj][m][0] * rinv, v1 = acc[ai][bj][m][1] * rinv;
; #pragma unroll
;                     for (int e = 0; e < 4; ++e) { const float a = fmaxf(v0[e], 0.f), b = fmaxf(v1[e], 0.f); v0[e] = a * a; v1[e] = b * b; }
;                     __builtin_nontemporal_store(pack8(v0, v1), (u32x4*)(rowp + bj * (4 * 512))); }
	v_max_f32_e32 v48, 0, v48
	v_max_f32_e32 v45, 0, v45
	v_max_f32_e32 v49, 0, v49
	v_pk_mul_f32 v[38:39], v[38:39], v[38:39]
	v_pk_mul_f32 v[52:53], v[34:35], v[34:35]
	v_pk_mul_f32 v[40:41], v[40:41], v[40:41]
	v_pk_mul_f32 v[56:57], v[36:37], v[36:37]
	v_pk_mul_f32 v[42:43], v[42:43], v[42:43]
	v_pk_mul_f32 v[46:47], v[46:47], v[46:47]
	v_pk_mul_f32 v[44:45], v[44:45], v[44:45]
	v_pk_mul_f32 v[48:49], v[48:49], v[48:49]
	v_cvt_pk_bf16_f32 v34, v38, v39
	v_cvt_pk_bf16_f32 v35, v40, v41
	v_cvt_pk_bf16_f32 v36, v52, v53
	v_cvt_pk_bf16_f32 v37, v56, v57
	v_cvt_pk_bf16_f32 v38, v42, v43
	v_cvt_pk_bf16_f32 v39, v44, v45
	v_cvt_pk_bf16_f32 v40, v46, v47
	v_cvt_pk_bf16_f32 v41, v48, v49
	global_store_dwordx4 v[50:51], v[34:37], off nt
	global_store_dwordx4 v[54:55], v[38:41], off nt
	s_nop 0
	v_add_u32_e32 v34, 0xa0, v150
	v_lshrrev_b32_e32 v34, 1, v34
	v_and_b32_e32 v34, 0x70, v34
	v_or_b32_e32 v34, s48, v34
	v_mov_b32_e32 v35, v139
	v_lshlrev_b32_e32 v34, 10, v34
	v_lshl_add_u64 v[34:35], s[28:29], 0, v[34:35]
	v_lshl_add_u64 v[34:35], v[34:35], 0, v[138:139]
	v_lshl_add_u64 v[34:35], v[34:35], 0, v[148:149]
	v_add_co_u32_e32 v38, vcc, s54, v34
	s_nop 0
	v_fmamk_f32 v36, v236, 0x3a800000, v158
	v_rsq_f32_e32 v36, v36
	v_addc_co_u32_e32 v39, vcc, 0, v35, vcc
	v_pk_mul_f32 v[24:25], v[24:25], v[36:37] op_sel_hi:[1,0]
	v_pk_mul_f32 v[22:23], v[22:23], v[36:37] op_sel_hi:[1,0]
	v_pk_mul_f32 v[20:21], v[20:21], v[36:37] op_sel_hi:[1,0]
	v_pk_mul_f32 v[18:19], v[18:19], v[36:37] op_sel_hi:[1,0]
	v_pk_mul_f32 v[28:29], v[28:29], v[36:37] op_sel_hi:[1,0]
	v_pk_mul_f32 v[26:27], v[26:27], v[36:37] op_sel_hi:[1,0]
	v_pk_mul_f32 v[32:33], v[32:33], v[36:37] op_sel_hi:[1,0]
	v_pk_mul_f32 v[30:31], v[30:31], v[36:37] op_sel_hi:[1,0]
	v_max_f32_e32 v22, 0, v22
	v_max_f32_e32 v18, 0, v18
	v_max_f32_e32 v23, 0, v23
	v_max_f32_e32 v19, 0, v19
	v_max_f32_e32 v24, 0, v24
	v_max_f32_e32 v20, 0, v20
	v_max_f32_e32 v25, 0, v25
	v_max_f32_e32 v21, 0, v21
	v_max_f32_e32 v26, 0, v26
	v_max_f32_e32 v30, 0, v30
	v_max_f32_e32 v27, 0, v27
	v_max_f32_e32 v31, 0, v31
	v_max_f32_e32 v28, 0, v28
	v_max_f32_e32 v32, 0, v32
	v_max_f32_e32 v29, 0, v29
	v_max_f32_e32 v33, 0, v33
	v_pk_mul_f32 v[22:23], v[22:23], v[22:23]
	v_pk_mul_f32 v[36:37], v[18:19], v[18:19]
	v_pk_mul_f32 v[24:25], v[24:25], v[24:25]
	v_pk_mul_f32 v[40:41], v[20:21], v[20:21]
	v_pk_mul_f32 v[26:27], v[26:27], v[26:27]
	v_pk_mul_f32 v[30:31], v[30:31], v[30:31]
	v_pk_mul_f32 v[28:29], v[28:29], v[28:29]
	v_pk_mul_f32 v[32:33], v[32:33], v[32:33]
	v_cvt_pk_bf16_f32 v18, v22, v23
	v_cvt_pk_bf16_f32 v19, v24, v25
	v_cvt_pk_bf16_f32 v20, v36, v37
	v_cvt_pk_bf16_f32 v21, v40, v41
	v_cvt_pk_bf16_f32 v22, v26, v27
	v_cvt_pk_bf16_f32 v23, v28, v29
	v_cvt_pk_bf16_f32 v24, v30, v31
	v_cvt_pk_bf16_f32 v25, v32, v33
	global_store_dwordx4 v[34:35], v[18:21], off nt
	global_store_dwordx4 v[38:39], v[22:25], off nt
	s_nop 0
	v_add_u32_e32 v18, 0xb0, v150
	v_lshrrev_b32_e32 v18, 1, v18
	v_and_b32_e32 v18, 0x78, v18
	v_or_b32_e32 v18, s48, v18
	v_mov_b32_e32 v19, v139
	v_lshlrev_b32_e32 v18, 10, v18
	v_lshl_add_u64 v[18:19], s[28:29], 0, v[18:19]
	v_lshl_add_u64 v[18:19], v[18:19], 0, v[138:139]
	v_lshl_add_u64 v[18:19], v[18:19], 0, v[148:149]
	v_add_co_u32_e32 v20, vcc, 0x1000, v18
	s_nop 0
	v_fmamk_f32 v21, v237, 0x3a800000, v158
	v_rsq_f32_e32 v22, v21
	v_addc_co_u32_e32 v21, vcc, 0, v19, vcc
	s_andn2_b64 vcc, exec, s[2:3]
	v_pk_mul_f32 v[8:9], v[8:9], v[22:23] op_sel_hi:[1,0]
	v_pk_mul_f32 v[6:7], v[6:7], v[22:23] op_sel_hi:[1,0]
	v_pk_mul_f32 v[4:5], v[4:5], v[22:23] op_sel_hi:[1,0]
	v_pk_mul_f32 v[2:3], v[2:3], v[22:23] op_sel_hi:[1,0]
	v_pk_mul_f32 v[12:13], v[12:13], v[22:23] op_sel_hi:[1,0]
	v_pk_mul_f32 v[10:11], v[10:11], v[22:23] op_sel_hi:[1,0]
	v_pk_mul_f32 v[16:17], v[16:17], v[22:23] op_sel_hi:[1,0]
	v_pk_mul_f32 v[14:15], v[14:15], v[22:23] op_sel_hi:[1,0]
	v_max_f32_e32 v6, 0, v6
	v_max_f32_e32 v2, 0, v2
	v_max_f32_e32 v7, 0, v7
	v_max_f32_e32 v3, 0, v3
	v_max_f32_e32 v8, 0, v8
	v_max_f32_e32 v4, 0, v4
	v_max_f32_e32 v9, 0, v9
	v_max_f32_e32 v5, 0, v5
	v_max_f32_e32 v10, 0, v10
	v_max_f32_e32 v14, 0, v14
	v_max_f32_e32 v11, 0, v11
	v_max_f32_e32 v15, 0, v15
	v_max_f32_e32 v12, 0, v12
	v_max_f32_e32 v16, 0, v16
	v_max_f32_e32 v13, 0, v13
	v_max_f32_e32 v17, 0, v17
	v_pk_mul_f32 v[6:7], v[6:7], v[6:7]
	v_pk_mul_f32 v[22:23], v[2:3], v[2:3]
	v_pk_mul_f32 v[8:9], v[8:9], v[8:9]
	v_pk_mul_f32 v[24:25], v[4:5], v[4:5]
	v_pk_mul_f32 v[10:11], v[10:11], v[10:11]
	v_pk_mul_f32 v[14:15], v[14:15], v[14:15]
	v_pk_mul_f32 v[12:13], v[12:13], v[12:13]
	v_pk_mul_f32 v[16:17], v[16:17], v[16:17]
	v_cvt_pk_bf16_f32 v2, v6, v7
	v_cvt_pk_bf16_f32 v3, v8, v9
	v_cvt_pk_bf16_f32 v4, v22, v23
	v_cvt_pk_bf16_f32 v5, v24, v25
	s_mov_b64 s[2:3], -1
	v_cvt_pk_bf16_f32 v6, v10, v11
	v_cvt_pk_bf16_f32 v7, v12, v13
	v_cvt_pk_bf16_f32 v8, v14, v15
	v_cvt_pk_bf16_f32 v9, v16, v17
	global_store_dwordx4 v[18:19], v[2:5], off nt
	global_store_dwordx4 v[20:21], v[6:9], off nt
	s_cbranch_vccnz .LBB0_792
	s_andn2_b64 vcc, exec, s[4:5]
	s_cbranch_vccnz .LBB0_791
	s_barrier
	s_branch .LBB0_791

; __global__ void __launch_bounds__(512, 2) fwd_kernel(Args args) {
	.amdhsa_kernel _Z10fwd_kernel4Args
		.amdhsa_group_segment_fixed_size 0
		.amdhsa_private_segment_fixed_size 0
		.amdhsa_kernarg_size 432
		.amdhsa_user_sgpr_count 2
		.amdhsa_user_sgpr_dispatch_ptr 0
		.amdhsa_user_sgpr_queue_ptr 0
		.amdhsa_user_sgpr_kernarg_segment_ptr 1
		.amdhsa_user_sgpr_dispatch_id 0
		.amdhsa_user_sgpr_kernarg_preload_length 0
		.amdhsa_user_sgpr_kernarg_preload_offset 0
		.amdhsa_user_sgpr_private_segment_size 0
		.amdhsa_uses_dynamic_stack 0
		.amdhsa_enable_private_segment 0
		.amdhsa_system_sgpr_workgroup_id_x 1
		.amdhsa_system_sgpr_workgroup_id_y 0
		.amdhsa_system_sgpr_workgroup_id_z 0
		.amdhsa_system_sgpr_workgroup_info 0
		.amdhsa_system_vgpr_workitem_id 0
		.amdhsa_next_free_vgpr 249
		.amdhsa_next_free_sgpr 102
		.amdhsa_accum_offset 252
		.amdhsa_reserve_vcc 1
		.amdhsa_float_round_mode_32 0
		.amdhsa_float_round_mode_16_64 0
		.amdhsa_float_denorm_mode_32 3
		.amdhsa_float_denorm_mode_16_64 3
		.amdhsa_dx10_clamp 1
		.amdhsa_ieee_mode 1
		.amdhsa_fp16_overflow 0
		.amdhsa_tg_split 0
		.amdhsa_exception_fp_ieee_invalid_op 0
		.amdhsa_exception_fp_denorm_src 0
		.amdhsa_exception_fp_ieee_div_zero 0
		.amdhsa_exception_fp_ieee_overflow 0
		.amdhsa_exception_fp_ieee_underflow 0
		.amdhsa_exception_fp_ieee_inexact 0
		.amdhsa_exception_int_div_zero 0
	.end_amdhsa_kernel

; __global__ void __launch_bounds__(512, 2) fwd_kernel(Args args) {
amdhsa.kernels:
  - .agpr_count:     0
    .args:
      - .offset:         0
        .size:           176
        .value_kind:     by_value
      - .offset:         176
        .size:           4
        .value_kind:     hidden_block_count_x
      - .offset:         180
        .size:           4
        .value_kind:     hidden_block_count_y
      - .offset:         184
        .size:           4
        .value_kind:     hidden_block_count_z
      - .offset:         188
        .size:           2
        .value_kind:     hidden_group_size_x
      - .offset:         190
        .size:           2
        .value_kind:     hidden_group_size_y
      - .offset:         192
        .size:           2
        .value_kind:     hidden_group_size_z
      - .offset:         194
        .size:           2
        .value_kind:     hidden_remainder_x
      - .offset:         196
        .size:           2
        .value_kind:     hidden_remainder_y
      - .offset:         198
        .size:           2
        .value_kind:     hidden_remainder_z
      - .offset:         216
        .size:           8
        .value_kind:     hidden_global_offset_x
      - .offset:         224
        .size:           8
        .value_kind:     hidden_global_offset_y
      - .offset:         232
        .size:           8
        .value_kind:     hidden_global_offset_z
      - .offset:         240
        .size:           2
        .value_kind:     hidden_grid_dims
      - .offset:         296
        .size:           4
        .value_kind:     hidden_dynamic_lds_size
    .group_segment_fixed_size: 0
    .kernarg_segment_align: 8
    .kernarg_segment_size: 432
    .language:       OpenCL C
    .language_version:
      - 2
      - 0
    .max_flat_workgroup_size: 512
    .name:           _Z10fwd_kernel4Args
    .private_segment_fixed_size: 0
    .sgpr_count:     108
    .sgpr_spill_count: 22
    .symbol:         _Z10fwd_kernel4Args.kd
    .uniform_work_group_size: 1
    .uses_dynamic_stack: false
    .vgpr_count:     249
    .vgpr_spill_count: 0
    .wavefront_size: 64
